# FoX: row-max subtraction folded into the QK MFMA chain as an extra K-slice (ones x -m, bf16-representable running stabiliser); 32 v_sub per tile removed
# baseline (speedup 1.0000x reference)
; __device__ __forceinline__ int crow(int r, int hi) { return (r & 3) + 8 * (r >> 2) + 4 * hi; }
; #define FX_STORE(bf) do { *(LAS u32x4*)(Kl + (2 * (bf)) * KBYTES + srow * KST + sch * 16) = kra; *(LAS u32x4*)(Kl + (2 * (bf) + 1) * KBYTES + srow * KST + sch * 16) = krb; \
;         *(LAS u32x4*)(Vl + (2 * (bf)) * KBYTES + srow * KST + sch * 16) = vra; *(LAS u32x4*)(Vl + (2 * (bf) + 1) * KBYTES + srow * KST + sch * 16) = vrb; if (tid < 128) Fl[(bf) * 128 + tid] = Fref - freg; } while (0)
; __device__ __forceinline__ void fox_tile(LAS const unsigned char* Kb, LAS const unsigned char* Vb, LAS const float* Fb, LAS float* wsf, const bf16x8 (&qr)[4], float Fq, int kt, int kt_my_last, int qw, ...
;     ...
;             if (kt == kt_my_last) { const int qrel = qw + r32 - kt * 64;
; #pragma unroll
;                 for (int r = 0; r < 16; ++r) { const int kv = crow(r, hi); if (kv > qrel) p0[r] = -INFINITY; if (kv + 32 > qrel) p1[r] = -INFINITY; } }
; __device__ __forceinline__ void fox_unit(const Params& p, LAS unsigned char* lds, int b, int h, int qb, float thr2) {
;     ...
;     const float Fq = 0.f, Fref = F2[q0];
;     int kt0 = 0, ktw = 0;
;     ...
;     { const float Fw = F2[qw]; const int ta = lane, tb = lane + 64;
;       const float fu = tid < NT - 4 ? F2[64 * tid + 63] : 0.f, fa = ta < NT - 4 ? F2[64 * ta + 63] : 0.f, fb = tb < NT - 4 ? F2[64 * tb + 63] : 0.f;
;       kt0 = __syncthreads_count((tid < NT - 4 && (fu - Fref) > thr2) ? 1 : 0);
;       const bool pa = ta < NT - 4 && (fa - Fw) > thr2, pb = tb < NT - 4 && (fb - Fw) > thr2;
;       ktw = __popcll(__ballot(pa)) + __popcll(__ballot(pb)); }
;     ...
;     float m_run = -INFINITY, l_run = 0.f; f32x16 o0, o1;
; #pragma unroll
;     for (int r = 0; r < 16; ++r) { o0[r] = 0.f; o1[r] = 0.f; }
;     const int st0 = kt0 >> 1;
;     FX_STORE(0); __syncthreads();
;     const int trq = (lane & 15) >> 2, trp = lane & 3;
.LBB0_1853:
	v_sub_f32_e32 v2, v5, v0
	v_cmp_gt_f32_e64 s[2:3], v2, v110
	v_sub_f32_e32 v0, v4, v0
	v_cmp_gt_f32_e64 s[12:13], v0, v110
	s_and_b64 s[2:3], vcc, s[2:3]
	v_cndmask_b32_e64 v0, 0, 1, s[2:3]
	s_and_b64 s[2:3], s[10:11], s[12:13]
	v_cmp_ne_u32_e32 vcc, 0, v0
	v_cndmask_b32_e64 v0, 0, 1, s[2:3]
	v_cmp_ne_u32_e64 s[10:11], 0, v0
	ds_write_b128 v111, v[66:69]
	ds_write_b128 v111, v[74:77] offset:9216
	ds_write_b128 v111, v[70:73] offset:36864
	ds_write_b128 v111, v[78:81] offset:46080
	s_and_saveexec_b64 s[2:3], s[6:7]
	v_sub_f32_e32 v0, v160, v107
	ds_write_b32 v112, v0
	s_or_b64 exec, exec, s[2:3]
	s_lshl_b32 s2, s16, 8
	s_add_i32 s33, s2, 0x100
	s_ashr_i32 s96, s17, 1
	s_add_i32 s33, s33, 0x12400
	s_cmp_le_i32 s9, s96
	v_lshl_add_u32 v161, v151, 2, s33
	s_waitcnt lgkmcnt(0)
	s_barrier
	s_cbranch_scc1 .LBB0_1886
	s_bcnt1_i32_b64 s2, vcc
	s_bcnt1_i32_b64 s97, s[10:11]
	v_and_or_b32 v0, s86, 32, v151
	s_add_i32 s97, s97, s2
	v_cmp_gt_u32_e64 s[10:11], v159, v0
	v_cmp_gt_u32_e64 s[12:13], v113, v0
	v_cmp_lt_u32_e64 s[14:15], v159, v0
	v_cmp_gt_u32_e64 s[16:17], v114, v0
	v_cmp_gt_u32_e64 s[18:19], v115, v0
	v_cmp_gt_u32_e64 s[20:21], v116, v0
	v_cmp_gt_u32_e64 s[22:23], v117, v0
	v_cmp_gt_u32_e64 s[24:25], v118, v0
	v_cmp_gt_u32_e64 s[26:27], v119, v0
	v_cmp_gt_u32_e64 s[28:29], v120, v0
	v_cmp_gt_u32_e64 s[30:31], v121, v0
	v_cmp_gt_u32_e64 s[34:35], v122, v0
	v_cmp_gt_u32_e64 s[36:37], v123, v0
	v_cmp_gt_u32_e64 s[38:39], v124, v0
	v_cmp_gt_u32_e64 s[40:41], v125, v0
	v_cmp_gt_u32_e64 s[42:43], v126, v0
	v_cmp_gt_u32_e64 s[44:45], v127, v0
	v_cmp_gt_u32_e64 s[46:47], v128, v0
	v_cmp_gt_u32_e64 s[48:49], v129, v0
	v_cmp_gt_u32_e64 s[50:51], v130, v0
	v_cmp_gt_u32_e64 s[52:53], v131, v0
	v_cmp_gt_u32_e64 s[54:55], v132, v0
	v_cmp_gt_u32_e64 s[56:57], v133, v0
	v_cmp_gt_u32_e64 s[58:59], v134, v0
	v_cmp_gt_u32_e64 s[60:61], v135, v0
	v_cmp_gt_u32_e64 s[62:63], v136, v0
	v_cmp_gt_u32_e64 s[64:65], v137, v0
	v_cmp_gt_u32_e64 s[66:67], v138, v0
	v_cmp_gt_u32_e64 s[68:69], v139, v0
	v_cmp_gt_u32_e64 s[70:71], v140, v0
	v_cmp_gt_u32_e64 s[72:73], v141, v0
	v_cmp_gt_u32_e64 s[74:75], v142, v0
	s_lshl_b32 s2, s9, 7
	v_add_u32_e32 v0, s86, v154
	v_add_u32_e32 v106, s2, v152
	v_subrev_u32_e32 v0, s2, v0
	s_lshl_b32 s2, s8, 8
	v_mov_b32_e32 v14, v1
	v_mov_b32_e32 v15, v1
	v_subrev_u32_e32 v163, s2, v0
	v_mov_b32_e32 v0, v1
	v_mov_b32_e32 v2, v1
	v_mov_b32_e32 v3, v1
	v_mov_b32_e32 v4, v1
	v_mov_b32_e32 v5, v1
	v_mov_b32_e32 v6, v1
	v_mov_b32_e32 v7, v1
	v_mov_b32_e32 v8, v1
	v_mov_b32_e32 v9, v1
	v_mov_b32_e32 v10, v1
	v_mov_b32_e32 v11, v1
	v_mov_b32_e32 v12, v1
	v_mov_b32_e32 v13, v1
	v_mov_b64_e32 v[32:33], v[14:15]
	s_lshr_b32 s84, s84, 6
	s_lshl_b32 s2, s8, 2
	v_mov_b64_e32 v[30:31], v[12:13]
	v_mov_b64_e32 v[28:29], v[10:11]
	v_mov_b64_e32 v[26:27], v[8:9]
	v_mov_b64_e32 v[24:25], v[6:7]
	v_mov_b64_e32 v[22:23], v[4:5]
	v_mov_b64_e32 v[20:21], v[2:3]
	v_mov_b64_e32 v[18:19], v[0:1]
	v_mov_b64_e32 v[16:17], v[14:15]
	s_sub_i32 s86, 0, s84
	s_sub_i32 s87, 0x7e, s2
	v_mov_b32_e32 v164, 0
	v_mov_b32_e32 v220, 0xff800000
	v_mov_b32_e32 v213, 0
	v_mov_b32_e32 v214, 0
	v_mov_b32_e32 v215, 0
	v_mov_b32_e32 v216, 0
	v_mov_b32_e32 v217, 0
	v_mov_b32_e32 v218, 0
	v_mov_b32_e32 v219, 0
	v_mov_b32_e32 v221, 0x3f80
	v_cndmask_b32_e64 v212, 0, v221, s[4:5]
	v_mov_b32_e32 v162, 0
	v_mov_b64_e32 v[14:15], v[12:13]
	v_mov_b64_e32 v[12:13], v[10:11]
	v_mov_b64_e32 v[10:11], v[8:9]
	v_mov_b64_e32 v[8:9], v[6:7]
	v_mov_b64_e32 v[6:7], v[4:5]
	v_mov_b64_e32 v[4:5], v[2:3]
	v_mov_b64_e32 v[2:3], v[0:1]

; #define LAS __attribute__((address_space(3)))
; __device__ __forceinline__ float ex2(float v) { return __builtin_amdgcn_exp2f(v); }
; __device__ __forceinline__ int crow(int r, int hi) { return (r & 3) + 8 * (r >> 2) + 4 * hi; }
; __device__ __forceinline__ f32x16 mfma32(bf16x8 a, bf16x8 b, f32x16 c) { return __builtin_amdgcn_mfma_f32_32x32x16_bf16(a, b, c, 0, 0, 0); }
; __device__ __forceinline__ void fox_tile(LAS const unsigned char* Kb, LAS const unsigned char* Vb, LAS const float* Fb, LAS float* wsf, const bf16x8 (&qr)[4], float Fq, int kt, int kt_my_last, int qw, ...
;     ...
;             f32x16 p0, p1;
; #pragma unroll
;             for (int g4 = 0; g4 < 4; ++g4) { const f32x4 fa = *(LAS const f32x4*)(Fb + 8 * g4 + 4 * hi), fb = *(LAS const f32x4*)(Fb + 32 + 8 * g4 + 4 * hi);
; #pragma unroll
;                 for (int i = 0; i < 4; ++i) { p0[4 * g4 + i] = fa[i]; p1[4 * g4 + i] = fb[i]; } }
; #pragma unroll
;             for (int d0 = 0; d0 < 4; ++d0) { const bf16x8 a0 = *(LAS const bf16x8*)(Kb + r32 * KST + (d0 * 16 + hi * 8) * 2), a1 = *(LAS const bf16x8*)(Kb + (32 + r32) * KST + (d0 * 16 + hi * 8) * 2);
;                 p0 = mfma32(a0, qr[d0], p0); p1 = mfma32(a1, qr[d0], p1); }
;             if (kt == kt_my_last) { const int qrel = qw + r32 - kt * 64;
; #pragma unroll
;                 for (int r = 0; r < 16; ++r) { const int kv = crow(r, hi); if (kv > qrel) p0[r] = -INFINITY; if (kv + 32 > qrel) p1[r] = -INFINITY; } }
;             float rm = fmaxf(p0[0], p1[0]);
; #pragma unroll
;             for (int r = 1; r < 16; ++r) rm = fmaxf(rm, fmaxf(p0[r], p1[r]));
;             rm = fmaxf(rm, __shfl_xor(rm, 32));
;             if (__any(rm > m_run)) {
;                 const float mn = fmaxf(m_run, rm); const float alpha = ex2(m_run - mn); m_run = mn; l_run *= alpha;
;                 if (hi == 0) wsf[r32] = alpha;
; #pragma unroll
;                 for (int g4 = 0; g4 < 4; ++g4) { const f32x4 al = *(LAS const f32x4*)(wsf + 8 * g4 + 4 * hi);
; #pragma unroll
;                     for (int i = 0; i < 4; ++i) { o0[4 * g4 + i] *= al[i]; o1[4 * g4 + i] *= al[i]; } } }
.LBB0_1861:
	s_and_b32 s9, s8, 1
	s_xor_b32 s88, s9, 1
	s_add_i32 s89, s86, s87
	s_add_i32 s78, s87, 1
	s_cmp_ge_i32 s78, s97
	s_cselect_b64 vcc, -1, 0
	s_cmp_lt_i32 s87, s84
	s_cselect_b64 s[94:95], -1, 0
	s_and_b64 s[94:95], vcc, s[94:95]
	s_mul_i32 s78, s88, 0x4800
	s_andn2_b64 vcc, exec, s[94:95]
	v_lshl_add_u32 v166, s88, 9, v147
	v_add_u32_e32 v165, s78, v148
	s_cbranch_vccnz .LBB0_1868
	ds_read_b128 v[54:57], v165 offset:9216
	ds_read_b128 v[34:37], v166 offset:256
	ds_read_b128 v[38:41], v166 offset:288
	ds_read_b128 v[42:45], v166 offset:320
	ds_read_b128 v[46:49], v166 offset:352
	ds_read_b128 v[168:171], v165 offset:13824
	ds_read_b128 v[50:53], v166 offset:384
	s_cmp_lg_u32 s89, -1
	s_waitcnt lgkmcnt(2)
	v_mfma_f32_32x32x16_bf16 v[34:49], v[54:57], v[82:85], v[34:49]
	ds_read_b128 v[54:57], v166 offset:416
	ds_read_b128 v[58:61], v166 offset:448
	ds_read_b128 v[62:65], v166 offset:480
	ds_read_b128 v[188:191], v165 offset:9248
	ds_read_b128 v[192:195], v165 offset:13856
	ds_read_b128 v[196:199], v165 offset:9280
	ds_read_b128 v[200:203], v165 offset:13888
	ds_read_b128 v[204:207], v165 offset:9312
	ds_read_b128 v[208:211], v165 offset:13920
	s_waitcnt lgkmcnt(6)
	v_mfma_f32_32x32x16_bf16 v[50:65], v[168:171], v[82:85], v[50:65]
	s_waitcnt lgkmcnt(5)
	v_mfma_f32_32x32x16_bf16 v[34:49], v[188:191], v[86:89], v[34:49]
	s_waitcnt lgkmcnt(4)
	v_mfma_f32_32x32x16_bf16 v[50:65], v[192:195], v[86:89], v[50:65]
	s_waitcnt lgkmcnt(3)
	v_mfma_f32_32x32x16_bf16 v[34:49], v[196:199], v[90:93], v[34:49]
	s_waitcnt lgkmcnt(2)
	v_mfma_f32_32x32x16_bf16 v[50:65], v[200:203], v[90:93], v[50:65]
	s_waitcnt lgkmcnt(1)
	v_mfma_f32_32x32x16_bf16 v[34:49], v[204:207], v[94:97], v[34:49]
	s_waitcnt lgkmcnt(0)
	v_mfma_f32_32x32x16_bf16 v[50:65], v[208:211], v[94:97], v[50:65]
	v_mfma_f32_32x32x16_bf16 v[34:49], v[212:215], v[216:219], v[34:49]
	v_mfma_f32_32x32x16_bf16 v[50:65], v[212:215], v[216:219], v[50:65]
	s_cbranch_scc1 .LBB0_1864
	s_nop 9
	v_cndmask_b32_e64 v0, v34, v158, s[10:11]
	s_nop 1
	v_cndmask_b32_e64 v50, v50, v158, s[12:13]
	v_cndmask_b32_e64 v35, v158, v35, s[14:15]
	v_cndmask_b32_e64 v34, v0, v34, s[14:15]
	v_cndmask_b32_e64 v51, v51, v158, s[16:17]
	v_cndmask_b32_e64 v36, v36, v158, s[18:19]
	v_cndmask_b32_e64 v52, v52, v158, s[20:21]
	v_cndmask_b32_e64 v37, v37, v158, s[22:23]
	v_cndmask_b32_e64 v53, v53, v158, s[24:25]
	v_cndmask_b32_e64 v38, v38, v158, s[26:27]
	v_cndmask_b32_e64 v54, v54, v158, s[28:29]
	v_cndmask_b32_e64 v39, v39, v158, s[30:31]
	v_cndmask_b32_e64 v55, v55, v158, s[34:35]
	v_cndmask_b32_e64 v40, v40, v158, s[36:37]
	v_cndmask_b32_e64 v56, v56, v158, s[38:39]
	v_cndmask_b32_e64 v41, v41, v158, s[40:41]
	v_cndmask_b32_e64 v57, v57, v158, s[42:43]
	v_cndmask_b32_e64 v42, v42, v158, s[44:45]
	v_cndmask_b32_e64 v58, v58, v158, s[46:47]
	v_cndmask_b32_e64 v43, v43, v158, s[48:49]
	v_cndmask_b32_e64 v59, v59, v158, s[50:51]
	v_cndmask_b32_e64 v44, v44, v158, s[52:53]
	v_cndmask_b32_e64 v60, v60, v158, s[54:55]
	v_cndmask_b32_e64 v45, v45, v158, s[56:57]
	v_cndmask_b32_e64 v61, v61, v158, s[58:59]
	v_cndmask_b32_e64 v46, v46, v158, s[60:61]
	v_cndmask_b32_e64 v62, v62, v158, s[62:63]
	v_cndmask_b32_e64 v47, v47, v158, s[64:65]
	v_cndmask_b32_e64 v63, v63, v158, s[66:67]
	v_cndmask_b32_e64 v48, v48, v158, s[68:69]
	v_cndmask_b32_e64 v64, v64, v158, s[70:71]
	v_cndmask_b32_e64 v49, v49, v158, s[72:73]
	v_cndmask_b32_e64 v65, v65, v158, s[74:75]
.LBB0_1864:
	s_nop 10
	v_max_f32_e32 v0, v35, v51
	v_max_f32_e32 v167, v36, v52
	v_max3_f32 v0, v34, v50, v0
	v_max_f32_e32 v168, v37, v53
	v_max3_f32 v0, v0, v167, v168
	v_max_f32_e32 v167, v38, v54
	v_max_f32_e32 v168, v39, v55
	v_max3_f32 v0, v0, v167, v168
	v_max_f32_e32 v167, v40, v56
	v_max_f32_e32 v168, v41, v57
	v_max3_f32 v0, v0, v167, v168
	v_max_f32_e32 v167, v42, v58
	v_max_f32_e32 v168, v43, v59
	v_max3_f32 v0, v0, v167, v168
	v_max_f32_e32 v167, v44, v60
	v_max_f32_e32 v168, v45, v61
	v_max3_f32 v0, v0, v167, v168
	v_max_f32_e32 v167, v46, v62
	v_max_f32_e32 v168, v47, v63
	v_max3_f32 v0, v0, v167, v168
	v_max_f32_e32 v167, v48, v64
	v_max_f32_e32 v168, v49, v65
	v_max3_f32 v0, v0, v167, v168
	ds_bpermute_b32 v167, v109, v0
	s_waitcnt lgkmcnt(0)
	v_max_f32_e32 v0, v0, v167
	v_cmp_gt_f32_e32 vcc, v0, v220
	s_cbranch_vccz .LBB0_1869
	v_max_f32_e32 v221, v0, v220
	v_add_f32_e32 v221, v164, v221
	v_cvt_pk_bf16_f32 v221, v221, v221
	v_lshlrev_b32_e32 v167, 16, v221
	v_sub_f32_e32 v222, v167, v164
	v_sub_f32_e32 v0, v164, v167
	v_exp_f32_e32 v0, v0
	v_xor_b32_e32 v223, 0x80000000, v167
	v_lshrrev_b32_e32 v223, 16, v223
	v_cndmask_b32_e64 v216, 0, v223, s[4:5]
	v_mov_b32_e32 v220, 0
	v_sub_f32_e32 v34, v34, v222
	v_sub_f32_e32 v35, v35, v222
	v_sub_f32_e32 v36, v36, v222
	v_sub_f32_e32 v37, v37, v222
	v_sub_f32_e32 v38, v38, v222
	v_sub_f32_e32 v39, v39, v222
	v_sub_f32_e32 v40, v40, v222
	v_sub_f32_e32 v41, v41, v222
	v_sub_f32_e32 v42, v42, v222
	v_sub_f32_e32 v43, v43, v222
	v_sub_f32_e32 v44, v44, v222
	v_sub_f32_e32 v45, v45, v222
	v_sub_f32_e32 v46, v46, v222
	v_sub_f32_e32 v47, v47, v222
	v_sub_f32_e32 v48, v48, v222
	v_sub_f32_e32 v49, v49, v222
	v_sub_f32_e32 v50, v50, v222
	v_sub_f32_e32 v51, v51, v222
	v_sub_f32_e32 v52, v52, v222
	v_sub_f32_e32 v53, v53, v222
	v_sub_f32_e32 v54, v54, v222
	v_sub_f32_e32 v55, v55, v222
	v_sub_f32_e32 v56, v56, v222
	v_sub_f32_e32 v57, v57, v222
	v_sub_f32_e32 v58, v58, v222
	v_sub_f32_e32 v59, v59, v222
	v_sub_f32_e32 v60, v60, v222
	v_sub_f32_e32 v61, v61, v222
	v_sub_f32_e32 v62, v62, v222
	v_sub_f32_e32 v63, v63, v222
	v_sub_f32_e32 v64, v64, v222
	v_sub_f32_e32 v65, v65, v222
	s_and_saveexec_b64 vcc, s[4:5]
	ds_write_b32 v161, v0
	s_or_b64 exec, exec, vcc
	v_mul_f32_e32 v162, v162, v0
	v_add_u32_e32 v0, s33, v153
	ds_read_b128 v[168:171], v0
	ds_read_b128 v[172:175], v0 offset:32
	ds_read_b128 v[176:179], v0 offset:64
	ds_read_b128 v[180:183], v0 offset:96
	s_waitcnt lgkmcnt(3)
	v_pk_mul_f32 v[20:21], v[20:21], v[170:171]
	s_waitcnt lgkmcnt(2)
	v_pk_mul_f32 v[22:23], v[22:23], v[172:173]
	s_waitcnt lgkmcnt(1)
	v_pk_mul_f32 v[26:27], v[26:27], v[176:177]
	s_waitcnt lgkmcnt(0)
	v_pk_mul_f32 v[30:31], v[30:31], v[180:181]
	v_pk_mul_f32 v[32:33], v[32:33], v[182:183]
	v_pk_mul_f32 v[28:29], v[28:29], v[178:179]
	v_pk_mul_f32 v[24:25], v[24:25], v[174:175]
	v_pk_mul_f32 v[18:19], v[18:19], v[168:169]
	v_pk_mul_f32 v[14:15], v[14:15], v[180:181]
	v_pk_mul_f32 v[10:11], v[10:11], v[176:177]
	v_pk_mul_f32 v[6:7], v[6:7], v[172:173]
	v_pk_mul_f32 v[16:17], v[16:17], v[182:183]
	v_pk_mul_f32 v[12:13], v[12:13], v[178:179]
	v_pk_mul_f32 v[8:9], v[8:9], v[174:175]
	v_pk_mul_f32 v[4:5], v[4:5], v[170:171]
	v_pk_mul_f32 v[2:3], v[2:3], v[168:169]
	s_branch .LBB0_1870

; __device__ __forceinline__ unsigned cvt_pk_bf16(float lo, float hi) { unsigned r; asm volatile("v_cvt_pk_bf16_f32 %0, %1, %2" : "=v"(r) : "v"(lo), "v"(hi)); return r; }
; #define LAS __attribute__((address_space(3)))
; __device__ __forceinline__ float ex2(float v) { return __builtin_amdgcn_exp2f(v); }
; __device__ __forceinline__ void fox_tile(LAS const unsigned char* Kb, LAS const unsigned char* Vb, LAS const float* Fb, LAS float* wsf, const bf16x8 (&qr)[4], float Fq, int kt, int kt_my_last, int qw, ...
;     ...
;             f32x16 p0, p1;
; #pragma unroll
;             for (int g4 = 0; g4 < 4; ++g4) { const f32x4 fa = *(LAS const f32x4*)(Fb + 8 * g4 + 4 * hi), fb = *(LAS const f32x4*)(Fb + 32 + 8 * g4 + 4 * hi);
; #pragma unroll
;                 for (int i = 0; i < 4; ++i) { p0[4 * g4 + i] = fa[i]; p1[4 * g4 + i] = fb[i]; } }
; #pragma unroll
;             for (int d0 = 0; d0 < 4; ++d0) { const bf16x8 a0 = *(LAS const bf16x8*)(Kb + r32 * KST + (d0 * 16 + hi * 8) * 2), a1 = *(LAS const bf16x8*)(Kb + (32 + r32) * KST + (d0 * 16 + hi * 8) * 2);
;                 p0 = mfma32(a0, qr[d0], p0); p1 = mfma32(a1, qr[d0], p1); }
;     ...
;             float sum = 0.f;
; #pragma unroll
;             for (int r = 0; r < 16; ++r) { p0[r] = ex2(p0[r] - m_run); p1[r] = ex2(p1[r] - m_run); sum += p0[r] + p1[r]; }
;             sum += __shfl_xor(sum, 32); l_run += sum;
;             bf16x8 pa[4];
; #pragma unroll
;             for (int s = 0; s < 2; ++s) { u32x4 w0, w1;
; #pragma unroll
;                 for (int e = 0; e < 4; ++e) { w0[e] = pg8::cvt_pk_bf16(p0[8 * s + 2 * e], p0[8 * s + 2 * e + 1]); w1[e] = pg8::cvt_pk_bf16(p1[8 * s + 2 * e], p1[8 * s + 2 * e + 1]); }
;                 pa[s] = __builtin_bit_cast(bf16x8, w0); pa[2 + s] = __builtin_bit_cast(bf16x8, w1); }
; #pragma unroll
;             for (int ks = 0; ks < 4; ++ks) {
; #pragma unroll
;                 for (int d0 = 0; d0 < 2; ++d0) { LAS const unsigned char* vp = Vb + (16 * ks + 4 * hi + trq) * KST + (32 * d0 + 16 * (r32 >> 4) + 4 * trp) * 2;
;                     const s16x4 lo = vtr(vp), hh = vtr(vp + 8 * KST);
;                     const bf16x8 vf = (bf16x8){lo[0], lo[1], lo[2], lo[3], hh[0], hh[1], hh[2], hh[3]};
;                     if (d0 == 0) o0 = mfma32(pa[ks], vf, o0); else o1 = mfma32(pa[ks], vf, o1); } }
.LBB0_1870:
	v_exp_f32_e32 v164, v34
	v_exp_f32_e32 v174, v50
	v_exp_f32_e32 v34, v35
	v_exp_f32_e32 v0, v51
	v_add_f32_e32 v35, v164, v174
	v_pk_add_f32 v[50:51], v[34:35], v[0:1]
	v_pk_add_f32 v[50:51], v[50:51], v[50:51] op_sel_hi:[0,1]
	v_exp_f32_e32 v35, v36
	v_exp_f32_e32 v175, v52
	v_exp_f32_e32 v36, v37
	v_exp_f32_e32 v50, v53
	v_add_f32_e32 v37, v35, v175
	v_cvt_pk_bf16_f32 v34, v164, v34
	v_pk_add_f32 v[52:53], v[36:37], v[50:51]
	v_exp_f32_e32 v51, v54
	v_pk_add_f32 v[52:53], v[52:53], v[52:53] op_sel_hi:[0,1]
	v_exp_f32_e32 v37, v38
	v_exp_f32_e32 v54, v39
	v_exp_f32_e32 v52, v55
	v_add_f32_e32 v55, v37, v51
	v_pk_add_f32 v[38:39], v[54:55], v[52:53]
	s_nop 0
	v_pk_add_f32 v[168:169], v[38:39], v[38:39] op_sel_hi:[0,1]
	v_exp_f32_e32 v53, v40
	v_exp_f32_e32 v55, v56
	v_exp_f32_e32 v56, v41
	v_exp_f32_e32 v168, v57
	v_add_f32_e32 v57, v53, v55
	v_pk_add_f32 v[38:39], v[56:57], v[168:169]
	s_nop 0
	v_pk_add_f32 v[170:171], v[38:39], v[38:39] op_sel_hi:[0,1]
	v_exp_f32_e32 v57, v42
	v_exp_f32_e32 v169, v58
	v_exp_f32_e32 v42, v43
	v_exp_f32_e32 v170, v59
	v_add_f32_e32 v43, v57, v169
	v_pk_add_f32 v[38:39], v[42:43], v[170:171]
	s_nop 0
	v_pk_add_f32 v[58:59], v[38:39], v[38:39] op_sel_hi:[0,1]
	v_exp_f32_e32 v43, v44
	v_exp_f32_e32 v171, v60
	v_exp_f32_e32 v44, v45
	v_exp_f32_e32 v58, v61
	v_add_f32_e32 v45, v43, v171
	v_pk_add_f32 v[38:39], v[44:45], v[58:59]
	s_nop 0
	v_pk_add_f32 v[60:61], v[38:39], v[38:39] op_sel_hi:[0,1]
	v_exp_f32_e32 v45, v46
	v_exp_f32_e32 v59, v62
	v_exp_f32_e32 v62, v47
	v_exp_f32_e32 v60, v63
	v_add_f32_e32 v63, v45, v59
	v_pk_add_f32 v[38:39], v[62:63], v[60:61]
	s_nop 0
	v_pk_add_f32 v[172:173], v[38:39], v[38:39] op_sel_hi:[0,1]
	v_exp_f32_e32 v61, v48
	v_exp_f32_e32 v63, v64
	v_exp_f32_e32 v64, v49
	v_exp_f32_e32 v172, v65
	v_cvt_pk_bf16_f32 v38, v174, v0
	v_add_u32_e32 v0, s78, v143
	v_cvt_pk_bf16_f32 v35, v35, v36
	v_cvt_pk_bf16_f32 v39, v175, v50
	v_cvt_pk_bf16_f32 v36, v37, v54
	v_cvt_pk_bf16_f32 v40, v51, v52
	v_cvt_pk_bf16_f32 v37, v53, v56
	v_cvt_pk_bf16_f32 v41, v55, v168
	v_cvt_pk_bf16_f32 v42, v57, v42
	v_cvt_pk_bf16_f32 v46, v169, v170
	v_cvt_pk_bf16_f32 v43, v43, v44
	v_cvt_pk_bf16_f32 v47, v171, v58
	v_cvt_pk_bf16_f32 v44, v45, v62
	v_cvt_pk_bf16_f32 v48, v59, v60
	v_cvt_pk_bf16_f32 v45, v61, v64
	v_cvt_pk_bf16_f32 v49, v63, v172
	ds_read_b64_tr_b16 v[50:51], v0 offset:46080
	ds_read_b64_tr_b16 v[52:53], v0 offset:47232
	ds_read_b64_tr_b16 v[56:57], v0 offset:47296
	ds_read_b64_tr_b16 v[54:55], v0 offset:46144
	s_waitcnt lgkmcnt(2)
	v_mfma_f32_32x32x16_bf16 v[18:33], v[34:37], v[50:53], v[18:33]
	v_add_f32_e32 v65, v61, v63
	s_waitcnt lgkmcnt(0)
	v_mfma_f32_32x32x16_bf16 v[2:17], v[34:37], v[54:57], v[2:17]
	ds_read_b64_tr_b16 v[34:35], v0 offset:48384
	ds_read_b64_tr_b16 v[36:37], v0 offset:49536
	ds_read_b64_tr_b16 v[52:53], v0 offset:49600
	ds_read_b64_tr_b16 v[50:51], v0 offset:48448
	s_waitcnt lgkmcnt(2)
	v_mfma_f32_32x32x16_bf16 v[18:33], v[42:45], v[34:37], v[18:33]
	s_waitcnt lgkmcnt(0)
	v_mfma_f32_32x32x16_bf16 v[2:17], v[42:45], v[50:53], v[2:17]
	ds_read_b64_tr_b16 v[34:35], v0 offset:50688
	ds_read_b64_tr_b16 v[36:37], v0 offset:51840
	ds_read_b64_tr_b16 v[44:45], v0 offset:51904
	ds_read_b64_tr_b16 v[42:43], v0 offset:50752
	s_waitcnt lgkmcnt(2)
	v_mfma_f32_32x32x16_bf16 v[18:33], v[38:41], v[34:37], v[18:33]
	ds_read_b64_tr_b16 v[34:35], v0 offset:52992
	ds_read_b64_tr_b16 v[36:37], v0 offset:54144
	s_waitcnt lgkmcnt(2)
	v_mfma_f32_32x32x16_bf16 v[2:17], v[38:41], v[42:45], v[2:17]
	v_add_f32_e64 v38, v64, v172
	v_add_f32_e64 v39, v65, v173
	v_add_f32_e32 v42, v38, v39
	ds_read_b64_tr_b16 v[40:41], v0 offset:54208
	ds_read_b64_tr_b16 v[38:39], v0 offset:53056
	ds_bpermute_b32 v0, v109, v42
	s_waitcnt lgkmcnt(0)
	v_add_f32_e32 v0, v42, v0
	v_mfma_f32_32x32x16_bf16 v[18:33], v[46:49], v[34:37], v[18:33]
	v_add_f32_e32 v162, v162, v0
	v_mfma_f32_32x32x16_bf16 v[2:17], v[46:49], v[38:41], v[2:17]
.LBB0_1871:
	s_cmp_lt_i32 s87, s97
	s_cselect_b64 s[94:95], -1, 0
	s_cmp_gt_i32 s87, s84
	s_cselect_b64 vcc, -1, 0
	s_or_b64 s[94:95], s[94:95], vcc
	s_and_b64 vcc, exec, s[94:95]
	s_cbranch_vccnz .LBB0_1878
	ds_read_b128 v[54:57], v165
	ds_read_b128 v[34:37], v166
	ds_read_b128 v[38:41], v166 offset:32
	ds_read_b128 v[42:45], v166 offset:64
	ds_read_b128 v[46:49], v166 offset:96
	ds_read_b128 v[168:171], v165 offset:4608
	ds_read_b128 v[50:53], v166 offset:128
	s_cmp_lg_u32 s89, 0
	s_waitcnt lgkmcnt(2)
	v_mfma_f32_32x32x16_bf16 v[34:49], v[54:57], v[82:85], v[34:49]
	ds_read_b128 v[54:57], v166 offset:160
	ds_read_b128 v[58:61], v166 offset:192
	ds_read_b128 v[62:65], v166 offset:224
	ds_read_b128 v[188:191], v165 offset:32
	ds_read_b128 v[192:195], v165 offset:4640
	ds_read_b128 v[196:199], v165 offset:64
	ds_read_b128 v[200:203], v165 offset:4672
	ds_read_b128 v[204:207], v165 offset:96
	ds_read_b128 v[208:211], v165 offset:4704
	s_waitcnt lgkmcnt(6)
	v_mfma_f32_32x32x16_bf16 v[50:65], v[168:171], v[82:85], v[50:65]
	s_waitcnt lgkmcnt(5)
	v_mfma_f32_32x32x16_bf16 v[34:49], v[188:191], v[86:89], v[34:49]
	s_waitcnt lgkmcnt(4)
	v_mfma_f32_32x32x16_bf16 v[50:65], v[192:195], v[86:89], v[50:65]
	s_waitcnt lgkmcnt(3)
	v_mfma_f32_32x32x16_bf16 v[34:49], v[196:199], v[90:93], v[34:49]
	s_waitcnt lgkmcnt(2)
	v_mfma_f32_32x32x16_bf16 v[50:65], v[200:203], v[90:93], v[50:65]
	s_waitcnt lgkmcnt(1)
	v_mfma_f32_32x32x16_bf16 v[34:49], v[204:207], v[94:97], v[34:49]
	s_waitcnt lgkmcnt(0)
	v_mfma_f32_32x32x16_bf16 v[50:65], v[208:211], v[94:97], v[50:65]
	v_mfma_f32_32x32x16_bf16 v[34:49], v[212:215], v[216:219], v[34:49]
	v_mfma_f32_32x32x16_bf16 v[50:65], v[212:215], v[216:219], v[50:65]
	s_cbranch_scc1 .LBB0_1874
; #define LAS __attribute__((address_space(3)))
; __device__ __forceinline__ float ex2(float v) { return __builtin_amdgcn_exp2f(v); }
; __device__ __forceinline__ int crow(int r, int hi) { return (r & 3) + 8 * (r >> 2) + 4 * hi; }
; __device__ __forceinline__ void fox_tile(LAS const unsigned char* Kb, LAS const unsigned char* Vb, LAS const float* Fb, LAS float* wsf, const bf16x8 (&qr)[4], float Fq, int kt, int kt_my_last, int qw, ...
;     ...
;             if (kt == kt_my_last) { const int qrel = qw + r32 - kt * 64;
; #pragma unroll
;                 for (int r = 0; r < 16; ++r) { const int kv = crow(r, hi); if (kv > qrel) p0[r] = -INFINITY; if (kv + 32 > qrel) p1[r] = -INFINITY; } }
;             float rm = fmaxf(p0[0], p1[0]);
; #pragma unroll
;             for (int r = 1; r < 16; ++r) rm = fmaxf(rm, fmaxf(p0[r], p1[r]));
;             rm = fmaxf(rm, __shfl_xor(rm, 32));
;             if (__any(rm > m_run)) {
;                 const float mn = fmaxf(m_run, rm); const float alpha = ex2(m_run - mn); m_run = mn; l_run *= alpha;
;                 if (hi == 0) wsf[r32] = alpha;
; #pragma unroll
;                 for (int g4 = 0; g4 < 4; ++g4) { const f32x4 al = *(LAS const f32x4*)(wsf + 8 * g4 + 4 * hi);
; #pragma unroll
;                     for (int i = 0; i < 4; ++i) { o0[4 * g4 + i] *= al[i]; o1[4 * g4 + i] *= al[i]; } } }
	v_cmp_le_i32_e32 vcc, v113, v163
	s_nop 9
	v_cndmask_b32_e32 v50, v158, v50, vcc
	v_cmp_lt_i32_e32 vcc, v159, v163
	s_nop 1
	v_cndmask_b32_e32 v35, v158, v35, vcc
	v_cmp_le_i32_e32 vcc, v159, v163
	s_nop 1
	v_cndmask_b32_e32 v34, v158, v34, vcc
	v_cmp_le_i32_e32 vcc, v114, v163
	s_nop 1
	v_cndmask_b32_e32 v51, v158, v51, vcc
	v_cmp_le_i32_e32 vcc, v115, v163
	s_nop 1
	v_cndmask_b32_e32 v36, v158, v36, vcc
	v_cmp_le_i32_e32 vcc, v116, v163
	s_nop 1
	v_cndmask_b32_e32 v52, v158, v52, vcc
	v_cmp_le_i32_e32 vcc, v117, v163
	s_nop 1
	v_cndmask_b32_e32 v37, v158, v37, vcc
	v_cmp_le_i32_e32 vcc, v118, v163
	s_nop 1
	v_cndmask_b32_e32 v53, v158, v53, vcc
	v_cmp_le_i32_e32 vcc, v119, v163
	s_nop 1
	v_cndmask_b32_e32 v38, v158, v38, vcc
	v_cmp_le_i32_e32 vcc, v120, v163
	s_nop 1
	v_cndmask_b32_e32 v54, v158, v54, vcc
	v_cmp_le_i32_e32 vcc, v121, v163
	s_nop 1
	v_cndmask_b32_e32 v39, v158, v39, vcc
	v_cmp_le_i32_e32 vcc, v122, v163
	s_nop 1
	v_cndmask_b32_e32 v55, v158, v55, vcc
	v_cmp_le_i32_e32 vcc, v123, v163
	s_nop 1
	v_cndmask_b32_e32 v40, v158, v40, vcc
	v_cmp_le_i32_e32 vcc, v124, v163
	s_nop 1
	v_cndmask_b32_e32 v56, v158, v56, vcc
	v_cmp_le_i32_e32 vcc, v125, v163
	s_nop 1
	v_cndmask_b32_e32 v41, v158, v41, vcc
	v_cmp_le_i32_e32 vcc, v126, v163
	s_nop 1
	v_cndmask_b32_e32 v57, v158, v57, vcc
	v_cmp_le_i32_e32 vcc, v127, v163
	s_nop 1
	v_cndmask_b32_e32 v42, v158, v42, vcc
	v_cmp_le_i32_e32 vcc, v128, v163
	s_nop 1
	v_cndmask_b32_e32 v58, v158, v58, vcc
	v_cmp_le_i32_e32 vcc, v129, v163
	s_nop 1
	v_cndmask_b32_e32 v43, v158, v43, vcc
	v_cmp_le_i32_e32 vcc, v130, v163
	s_nop 1
	v_cndmask_b32_e32 v59, v158, v59, vcc
	v_cmp_le_i32_e32 vcc, v131, v163
	s_nop 1
	v_cndmask_b32_e32 v44, v158, v44, vcc
	v_cmp_le_i32_e32 vcc, v132, v163
	s_nop 1
	v_cndmask_b32_e32 v60, v158, v60, vcc
	v_cmp_le_i32_e32 vcc, v133, v163
	s_nop 1
	v_cndmask_b32_e32 v45, v158, v45, vcc
	v_cmp_le_i32_e32 vcc, v134, v163
	s_nop 1
	v_cndmask_b32_e32 v61, v158, v61, vcc
	v_cmp_le_i32_e32 vcc, v135, v163
	s_nop 1
	v_cndmask_b32_e32 v46, v158, v46, vcc
	v_cmp_le_i32_e32 vcc, v136, v163
	s_nop 1
	v_cndmask_b32_e32 v62, v158, v62, vcc
	v_cmp_le_i32_e32 vcc, v137, v163
	s_nop 1
	v_cndmask_b32_e32 v47, v158, v47, vcc
	v_cmp_le_i32_e32 vcc, v138, v163
	s_nop 1
	v_cndmask_b32_e32 v63, v158, v63, vcc
	v_cmp_le_i32_e32 vcc, v139, v163
	s_nop 1
	v_cndmask_b32_e32 v48, v158, v48, vcc
	v_cmp_le_i32_e32 vcc, v140, v163
	s_nop 1
	v_cndmask_b32_e32 v64, v158, v64, vcc
	v_cmp_le_i32_e32 vcc, v141, v163
	s_nop 1
	v_cndmask_b32_e32 v49, v158, v49, vcc
	v_cmp_le_i32_e32 vcc, v142, v163
	s_nop 1
	v_cndmask_b32_e32 v65, v158, v65, vcc
.LBB0_1874:
	s_nop 10
	v_max_f32_e32 v0, v35, v51
	v_max_f32_e32 v164, v36, v52
	v_max3_f32 v0, v34, v50, v0
	v_max_f32_e32 v165, v37, v53
	v_max3_f32 v0, v0, v164, v165
	v_max_f32_e32 v164, v38, v54
	v_max_f32_e32 v165, v39, v55
	v_max3_f32 v0, v0, v164, v165
	v_max_f32_e32 v164, v40, v56
	v_max_f32_e32 v165, v41, v57
	v_max3_f32 v0, v0, v164, v165
	v_max_f32_e32 v164, v42, v58
	v_max_f32_e32 v165, v43, v59
	v_max3_f32 v0, v0, v164, v165
	v_max_f32_e32 v164, v44, v60
	v_max_f32_e32 v165, v45, v61
	v_max3_f32 v0, v0, v164, v165
	v_max_f32_e32 v164, v46, v62
	v_max_f32_e32 v165, v47, v63
	v_max3_f32 v0, v0, v164, v165
	v_max_f32_e32 v164, v48, v64
	v_max_f32_e32 v165, v49, v65
	v_max3_f32 v0, v0, v164, v165
	ds_bpermute_b32 v164, v109, v0
	s_waitcnt lgkmcnt(0)
	v_max_f32_e32 v0, v0, v164
	v_cmp_gt_f32_e32 vcc, v0, v220
	s_cbranch_vccz .LBB0_1879
	v_max_f32_e32 v221, v0, v220
	v_add_f32_e32 v221, v167, v221
	v_cvt_pk_bf16_f32 v221, v221, v221
	v_lshlrev_b32_e32 v164, 16, v221
	v_sub_f32_e32 v222, v164, v167
	v_sub_f32_e32 v0, v167, v164
	v_exp_f32_e32 v0, v0
	v_xor_b32_e32 v223, 0x80000000, v164
	v_lshrrev_b32_e32 v223, 16, v223
	v_cndmask_b32_e64 v216, 0, v223, s[4:5]
	v_mov_b32_e32 v220, 0
	v_sub_f32_e32 v34, v34, v222
	v_sub_f32_e32 v35, v35, v222
	v_sub_f32_e32 v36, v36, v222
	v_sub_f32_e32 v37, v37, v222
	v_sub_f32_e32 v38, v38, v222
	v_sub_f32_e32 v39, v39, v222
	v_sub_f32_e32 v40, v40, v222
	v_sub_f32_e32 v41, v41, v222
	v_sub_f32_e32 v42, v42, v222
	v_sub_f32_e32 v43, v43, v222
	v_sub_f32_e32 v44, v44, v222
	v_sub_f32_e32 v45, v45, v222
	v_sub_f32_e32 v46, v46, v222
	v_sub_f32_e32 v47, v47, v222
	v_sub_f32_e32 v48, v48, v222
	v_sub_f32_e32 v49, v49, v222
	v_sub_f32_e32 v50, v50, v222
	v_sub_f32_e32 v51, v51, v222
	v_sub_f32_e32 v52, v52, v222
	v_sub_f32_e32 v53, v53, v222
	v_sub_f32_e32 v54, v54, v222
	v_sub_f32_e32 v55, v55, v222
	v_sub_f32_e32 v56, v56, v222
	v_sub_f32_e32 v57, v57, v222
	v_sub_f32_e32 v58, v58, v222
	v_sub_f32_e32 v59, v59, v222
	v_sub_f32_e32 v60, v60, v222
	v_sub_f32_e32 v61, v61, v222
	v_sub_f32_e32 v62, v62, v222
	v_sub_f32_e32 v63, v63, v222
	v_sub_f32_e32 v64, v64, v222
	v_sub_f32_e32 v65, v65, v222
	s_and_saveexec_b64 vcc, s[4:5]
	ds_write_b32 v161, v0
	s_or_b64 exec, exec, vcc
	v_mul_f32_e32 v162, v162, v0
	v_add_u32_e32 v0, s33, v153
	ds_read_b128 v[166:169], v0
	ds_read_b128 v[170:173], v0 offset:32
	ds_read_b128 v[174:177], v0 offset:64
	ds_read_b128 v[178:181], v0 offset:96
	s_waitcnt lgkmcnt(3)
	v_pk_mul_f32 v[20:21], v[20:21], v[168:169]
	s_waitcnt lgkmcnt(2)
	v_pk_mul_f32 v[22:23], v[22:23], v[170:171]
	s_waitcnt lgkmcnt(1)
	v_pk_mul_f32 v[26:27], v[26:27], v[174:175]
	s_waitcnt lgkmcnt(0)
	v_pk_mul_f32 v[30:31], v[30:31], v[178:179]
	v_pk_mul_f32 v[32:33], v[32:33], v[180:181]
	v_pk_mul_f32 v[28:29], v[28:29], v[176:177]
	v_pk_mul_f32 v[24:25], v[24:25], v[172:173]
	v_pk_mul_f32 v[18:19], v[18:19], v[166:167]
	v_pk_mul_f32 v[14:15], v[14:15], v[178:179]
	v_pk_mul_f32 v[10:11], v[10:11], v[174:175]
	v_pk_mul_f32 v[6:7], v[6:7], v[170:171]
	v_pk_mul_f32 v[16:17], v[16:17], v[180:181]
	v_pk_mul_f32 v[12:13], v[12:13], v[176:177]
	v_pk_mul_f32 v[8:9], v[8:9], v[172:173]
	v_pk_mul_f32 v[4:5], v[4:5], v[168:169]
	v_pk_mul_f32 v[2:3], v[2:3], v[166:167]
	s_branch .LBB0_1880

; __device__ __forceinline__ unsigned cvt_pk_bf16(float lo, float hi) { unsigned r; asm volatile("v_cvt_pk_bf16_f32 %0, %1, %2" : "=v"(r) : "v"(lo), "v"(hi)); return r; }
; #define LAS __attribute__((address_space(3)))
; __device__ __forceinline__ float ex2(float v) { return __builtin_amdgcn_exp2f(v); }
; __device__ __forceinline__ f32x16 mfma32(bf16x8 a, bf16x8 b, f32x16 c) { return __builtin_amdgcn_mfma_f32_32x32x16_bf16(a, b, c, 0, 0, 0); }
; __device__ __forceinline__ s16x4 vtr(LAS const unsigned char* pp) { return __builtin_bit_cast(s16x4, __builtin_amdgcn_ds_read_tr16_b64_v4i16((LAS s16x4*)pp)); }
; __device__ __forceinline__ void fox_tile(LAS const unsigned char* Kb, LAS const unsigned char* Vb, LAS const float* Fb, LAS float* wsf, const bf16x8 (&qr)[4], float Fq, int kt, int kt_my_last, int qw, ...
;     ...
;             float sum = 0.f;
; #pragma unroll
;             for (int r = 0; r < 16; ++r) { p0[r] = ex2(p0[r] - m_run); p1[r] = ex2(p1[r] - m_run); sum += p0[r] + p1[r]; }
;             sum += __shfl_xor(sum, 32); l_run += sum;
;             bf16x8 pa[4];
; #pragma unroll
;             for (int s = 0; s < 2; ++s) { u32x4 w0, w1;
; #pragma unroll
;                 for (int e = 0; e < 4; ++e) { w0[e] = pg8::cvt_pk_bf16(p0[8 * s + 2 * e], p0[8 * s + 2 * e + 1]); w1[e] = pg8::cvt_pk_bf16(p1[8 * s + 2 * e], p1[8 * s + 2 * e + 1]); }
;                 pa[s] = __builtin_bit_cast(bf16x8, w0); pa[2 + s] = __builtin_bit_cast(bf16x8, w1); }
; #pragma unroll
;             for (int ks = 0; ks < 4; ++ks) {
; #pragma unroll
;                 for (int d0 = 0; d0 < 2; ++d0) { LAS const unsigned char* vp = Vb + (16 * ks + 4 * hi + trq) * KST + (32 * d0 + 16 * (r32 >> 4) + 4 * trp) * 2;
;                     const s16x4 lo = vtr(vp), hh = vtr(vp + 8 * KST);
;                     const bf16x8 vf = (bf16x8){lo[0], lo[1], lo[2], lo[3], hh[0], hh[1], hh[2], hh[3]};
;                     if (d0 == 0) o0 = mfma32(pa[ks], vf, o0); else o1 = mfma32(pa[ks], vf, o1); } }
.LBB0_1880:
	v_exp_f32_e32 v165, v34
	v_exp_f32_e32 v172, v50
	v_exp_f32_e32 v34, v35
	v_exp_f32_e32 v0, v51
	v_add_f32_e32 v35, v165, v172
	v_pk_add_f32 v[50:51], v[34:35], v[0:1]
	v_pk_add_f32 v[50:51], v[50:51], v[50:51] op_sel_hi:[0,1]
	v_exp_f32_e32 v35, v36
	v_exp_f32_e32 v173, v52
	v_exp_f32_e32 v36, v37
	v_exp_f32_e32 v50, v53
	v_add_f32_e32 v37, v35, v173
	v_cvt_pk_bf16_f32 v34, v165, v34
	v_pk_add_f32 v[52:53], v[36:37], v[50:51]
	v_exp_f32_e32 v51, v54
	v_pk_add_f32 v[52:53], v[52:53], v[52:53] op_sel_hi:[0,1]
	v_exp_f32_e32 v37, v38
	v_exp_f32_e32 v54, v39
	v_exp_f32_e32 v52, v55
	v_add_f32_e32 v55, v37, v51
	v_pk_add_f32 v[38:39], v[54:55], v[52:53]
	s_nop 0
	v_pk_add_f32 v[166:167], v[38:39], v[38:39] op_sel_hi:[0,1]
	v_exp_f32_e32 v53, v40
	v_exp_f32_e32 v55, v56
	v_exp_f32_e32 v56, v41
	v_exp_f32_e32 v166, v57
	v_add_f32_e32 v57, v53, v55
	v_pk_add_f32 v[38:39], v[56:57], v[166:167]
	s_nop 0
	v_pk_add_f32 v[168:169], v[38:39], v[38:39] op_sel_hi:[0,1]
	v_exp_f32_e32 v57, v42
	v_exp_f32_e32 v167, v58
	v_exp_f32_e32 v42, v43
	v_exp_f32_e32 v168, v59
	v_add_f32_e32 v43, v57, v167
	v_pk_add_f32 v[38:39], v[42:43], v[168:169]
	s_nop 0
	v_pk_add_f32 v[58:59], v[38:39], v[38:39] op_sel_hi:[0,1]
	v_exp_f32_e32 v43, v44
	v_exp_f32_e32 v169, v60
	v_exp_f32_e32 v44, v45
	v_exp_f32_e32 v58, v61
	v_add_f32_e32 v45, v43, v169
	v_pk_add_f32 v[38:39], v[44:45], v[58:59]
	s_nop 0
	v_pk_add_f32 v[60:61], v[38:39], v[38:39] op_sel_hi:[0,1]
	v_exp_f32_e32 v45, v46
	v_exp_f32_e32 v59, v62
	v_exp_f32_e32 v62, v47
	v_exp_f32_e32 v60, v63
	v_add_f32_e32 v63, v45, v59
	v_pk_add_f32 v[38:39], v[62:63], v[60:61]
	s_nop 0
	v_pk_add_f32 v[170:171], v[38:39], v[38:39] op_sel_hi:[0,1]
	v_exp_f32_e32 v61, v48
	v_exp_f32_e32 v63, v64
	v_exp_f32_e32 v64, v49
	v_exp_f32_e32 v170, v65
	v_cvt_pk_bf16_f32 v38, v172, v0
	v_add_u32_e32 v0, s78, v143
	v_cvt_pk_bf16_f32 v35, v35, v36
	v_cvt_pk_bf16_f32 v39, v173, v50
	v_cvt_pk_bf16_f32 v36, v37, v54
	v_cvt_pk_bf16_f32 v40, v51, v52
	v_cvt_pk_bf16_f32 v37, v53, v56
	v_cvt_pk_bf16_f32 v41, v55, v166
	v_cvt_pk_bf16_f32 v42, v57, v42
	v_cvt_pk_bf16_f32 v46, v167, v168
	v_cvt_pk_bf16_f32 v43, v43, v44
	v_cvt_pk_bf16_f32 v47, v169, v58
	v_cvt_pk_bf16_f32 v44, v45, v62
	v_cvt_pk_bf16_f32 v48, v59, v60
	v_cvt_pk_bf16_f32 v45, v61, v64
	v_cvt_pk_bf16_f32 v49, v63, v170
	ds_read_b64_tr_b16 v[50:51], v0 offset:36864
	ds_read_b64_tr_b16 v[52:53], v0 offset:38016
	ds_read_b64_tr_b16 v[56:57], v0 offset:38080
	ds_read_b64_tr_b16 v[54:55], v0 offset:36928
	s_waitcnt lgkmcnt(2)
	v_mfma_f32_32x32x16_bf16 v[18:33], v[34:37], v[50:53], v[18:33]
	v_add_f32_e32 v65, v61, v63
	s_waitcnt lgkmcnt(0)
	v_mfma_f32_32x32x16_bf16 v[2:17], v[34:37], v[54:57], v[2:17]
	ds_read_b64_tr_b16 v[34:35], v0 offset:39168
	ds_read_b64_tr_b16 v[36:37], v0 offset:40320
	ds_read_b64_tr_b16 v[52:53], v0 offset:40384
	ds_read_b64_tr_b16 v[50:51], v0 offset:39232
	s_waitcnt lgkmcnt(2)
	v_mfma_f32_32x32x16_bf16 v[18:33], v[42:45], v[34:37], v[18:33]
	s_waitcnt lgkmcnt(0)
	v_mfma_f32_32x32x16_bf16 v[2:17], v[42:45], v[50:53], v[2:17]
	ds_read_b64_tr_b16 v[34:35], v0 offset:41472
	ds_read_b64_tr_b16 v[36:37], v0 offset:42624
	ds_read_b64_tr_b16 v[44:45], v0 offset:42688
	ds_read_b64_tr_b16 v[42:43], v0 offset:41536
	s_waitcnt lgkmcnt(2)
	v_mfma_f32_32x32x16_bf16 v[18:33], v[38:41], v[34:37], v[18:33]
	ds_read_b64_tr_b16 v[34:35], v0 offset:43776
	ds_read_b64_tr_b16 v[36:37], v0 offset:44928
	s_waitcnt lgkmcnt(2)
	v_mfma_f32_32x32x16_bf16 v[2:17], v[38:41], v[42:45], v[2:17]
	v_add_f32_e64 v38, v64, v170
	v_add_f32_e64 v39, v65, v171
	v_add_f32_e32 v42, v38, v39
	ds_read_b64_tr_b16 v[40:41], v0 offset:44992
	ds_read_b64_tr_b16 v[38:39], v0 offset:43840
	ds_bpermute_b32 v0, v109, v42
	s_waitcnt lgkmcnt(0)
	v_add_f32_e32 v0, v42, v0
	v_mfma_f32_32x32x16_bf16 v[18:33], v[46:49], v[34:37], v[18:33]
	v_add_f32_e32 v162, v162, v0
	v_mfma_f32_32x32x16_bf16 v[2:17], v[46:49], v[38:41], v[2:17]
	s_andn2_b64 vcc, exec, s[92:93]
	s_cbranch_vccnz .LBB0_1884
